# PEER stage B: rstd folded into the DOTS accumulate (xn = h*g), single pk_fma chain per piece (no pk_add)
# speedup vs baseline: 1.0088x; 1.0022x over previous
.Lpb_unit:
	s_lshl_b32 s0, s17, 11
	s_add_i32 s0, s0, s27
	s_cmp_eq_u32 s17, 8
	s_cselect_b32 s0, s44, s0
	s_lshl_b32 s1, s16, 9
	s_lshl_b32 s24, s0, 12
	s_add_u32 s24, s24, s1
	s_add_u32 s20, s4, s24
	s_addc_u32 s21, s5, 0
	s_add_u32 s36, s6, s1
	s_addc_u32 s37, s7, 0
	s_lshl_b32 s25, s16, 21
	s_add_u32 s18, s8, s25
	s_addc_u32 s19, s9, 0
	s_lshl_b32 s25, s17, 9
	v_add_u32_e32 v205, s25, v190
	v_add_u32_e32 v210, s25, v209
	s_lshl_b32 s25, s17, 2
	v_add_u32_e32 v206, s25, v204
	ds_read_b128 v[64:67], v205
	ds_read_b128 v[68:71], v205 offset:16
	ds_read_b128 v[72:75], v205 offset:32
	ds_read_b128 v[76:79], v205 offset:48
	ds_read_b32 v208, v206
	global_load_dwordx4 v[80:83], v189, s[20:21]
	global_load_dwordx4 v[84:87], v189, s[20:21] offset:16
	global_load_dwordx4 v[88:91], v189, s[20:21] offset:32
	global_load_dwordx4 v[92:95], v189, s[20:21] offset:48
	s_waitcnt lgkmcnt(1)
	v_add_u32_e32 v64, v64, v188
	v_add_u32_e32 v65, v65, v188
	v_add_u32_e32 v66, v66, v188
	v_add_u32_e32 v67, v67, v188
	v_add_u32_e32 v68, v68, v188
	v_add_u32_e32 v69, v69, v188
	v_add_u32_e32 v70, v70, v188
	v_add_u32_e32 v71, v71, v188
	v_add_u32_e32 v72, v72, v188
	v_add_u32_e32 v73, v73, v188
	v_add_u32_e32 v74, v74, v188
	v_add_u32_e32 v75, v75, v188
	v_add_u32_e32 v76, v76, v188
	v_add_u32_e32 v77, v77, v188
	v_add_u32_e32 v78, v78, v188
	v_add_u32_e32 v79, v79, v188
	global_load_dwordx4 v[0:3], v64, s[18:19]
	global_load_dwordx4 v[4:7], v65, s[18:19]
	global_load_dwordx4 v[8:11], v66, s[18:19]
	global_load_dwordx4 v[12:15], v67, s[18:19]
	global_load_dwordx4 v[16:19], v68, s[18:19]
	global_load_dwordx4 v[20:23], v69, s[18:19]
	global_load_dwordx4 v[24:27], v70, s[18:19]
	global_load_dwordx4 v[28:31], v71, s[18:19]
	global_load_dwordx4 v[32:35], v72, s[18:19]
	global_load_dwordx4 v[36:39], v73, s[18:19]
	global_load_dwordx4 v[40:43], v74, s[18:19]
	global_load_dwordx4 v[44:47], v75, s[18:19]
	global_load_dwordx4 v[48:51], v76, s[18:19]
	global_load_dwordx4 v[52:55], v77, s[18:19]
	global_load_dwordx4 v[56:59], v78, s[18:19]
	global_load_dwordx4 v[60:63], v79, s[18:19]
	s_waitcnt vmcnt(16) lgkmcnt(0)
	v_pk_mul_f32 v[80:81], v[80:81], v[128:129]
	v_pk_mul_f32 v[82:83], v[82:83], v[130:131]
	v_pk_mul_f32 v[84:85], v[84:85], v[132:133]
	v_pk_mul_f32 v[86:87], v[86:87], v[134:135]
	v_pk_mul_f32 v[88:89], v[88:89], v[136:137]
	v_pk_mul_f32 v[90:91], v[90:91], v[138:139]
	v_pk_mul_f32 v[92:93], v[92:93], v[140:141]
	v_pk_mul_f32 v[94:95], v[94:95], v[142:143]
	s_waitcnt vmcnt(15)
	v_cvt_pk_f32_fp8_e32 v[168:169], v0
	v_cvt_pk_f32_fp8_sdwa v[170:171], v0 src0_sel:WORD_1
	v_cvt_pk_f32_fp8_e32 v[172:173], v1
	v_cvt_pk_f32_fp8_sdwa v[174:175], v1 src0_sel:WORD_1
	v_cvt_pk_f32_fp8_e32 v[176:177], v2
	v_cvt_pk_f32_fp8_sdwa v[178:179], v2 src0_sel:WORD_1
	v_cvt_pk_f32_fp8_e32 v[180:181], v3
	v_cvt_pk_f32_fp8_sdwa v[182:183], v3 src0_sel:WORD_1
	v_pk_mul_f32 v[184:185], v[168:169], v[80:81]
	v_pk_fma_f32 v[184:185], v[170:171], v[82:83], v[184:185]
	v_pk_fma_f32 v[184:185], v[172:173], v[84:85], v[184:185]
	v_pk_fma_f32 v[184:185], v[174:175], v[86:87], v[184:185]
	v_pk_fma_f32 v[184:185], v[176:177], v[88:89], v[184:185]
	v_pk_fma_f32 v[184:185], v[178:179], v[90:91], v[184:185]
	v_pk_fma_f32 v[184:185], v[180:181], v[92:93], v[184:185]
	v_pk_fma_f32 v[184:185], v[182:183], v[94:95], v[184:185]
	v_add_f32_e32 v112, v184, v185
	s_waitcnt vmcnt(14)
	v_cvt_pk_f32_fp8_e32 v[168:169], v4
	v_cvt_pk_f32_fp8_sdwa v[170:171], v4 src0_sel:WORD_1
	v_cvt_pk_f32_fp8_e32 v[172:173], v5
	v_cvt_pk_f32_fp8_sdwa v[174:175], v5 src0_sel:WORD_1
	v_cvt_pk_f32_fp8_e32 v[176:177], v6
	v_cvt_pk_f32_fp8_sdwa v[178:179], v6 src0_sel:WORD_1
	v_cvt_pk_f32_fp8_e32 v[180:181], v7
	v_cvt_pk_f32_fp8_sdwa v[182:183], v7 src0_sel:WORD_1
	v_pk_mul_f32 v[186:187], v[168:169], v[80:81]
	v_pk_fma_f32 v[186:187], v[170:171], v[82:83], v[186:187]
	v_pk_fma_f32 v[186:187], v[172:173], v[84:85], v[186:187]
	v_pk_fma_f32 v[186:187], v[174:175], v[86:87], v[186:187]
	v_pk_fma_f32 v[186:187], v[176:177], v[88:89], v[186:187]
	v_pk_fma_f32 v[186:187], v[178:179], v[90:91], v[186:187]
	v_pk_fma_f32 v[186:187], v[180:181], v[92:93], v[186:187]
	v_pk_fma_f32 v[186:187], v[182:183], v[94:95], v[186:187]
	v_add_f32_e32 v113, v186, v187
	s_waitcnt vmcnt(13)
	v_cvt_pk_f32_fp8_e32 v[168:169], v8
	v_cvt_pk_f32_fp8_sdwa v[170:171], v8 src0_sel:WORD_1
	v_cvt_pk_f32_fp8_e32 v[172:173], v9
	v_cvt_pk_f32_fp8_sdwa v[174:175], v9 src0_sel:WORD_1
	v_cvt_pk_f32_fp8_e32 v[176:177], v10
	v_cvt_pk_f32_fp8_sdwa v[178:179], v10 src0_sel:WORD_1
	v_cvt_pk_f32_fp8_e32 v[180:181], v11
	v_cvt_pk_f32_fp8_sdwa v[182:183], v11 src0_sel:WORD_1
	v_pk_mul_f32 v[184:185], v[168:169], v[80:81]
	v_pk_fma_f32 v[184:185], v[170:171], v[82:83], v[184:185]
	v_pk_fma_f32 v[184:185], v[172:173], v[84:85], v[184:185]
	v_pk_fma_f32 v[184:185], v[174:175], v[86:87], v[184:185]
	v_pk_fma_f32 v[184:185], v[176:177], v[88:89], v[184:185]
	v_pk_fma_f32 v[184:185], v[178:179], v[90:91], v[184:185]
	v_pk_fma_f32 v[184:185], v[180:181], v[92:93], v[184:185]
	v_pk_fma_f32 v[184:185], v[182:183], v[94:95], v[184:185]
	v_add_f32_e32 v114, v184, v185
	s_waitcnt vmcnt(12)
	v_cvt_pk_f32_fp8_e32 v[168:169], v12
	v_cvt_pk_f32_fp8_sdwa v[170:171], v12 src0_sel:WORD_1
	v_cvt_pk_f32_fp8_e32 v[172:173], v13
	v_cvt_pk_f32_fp8_sdwa v[174:175], v13 src0_sel:WORD_1
	v_cvt_pk_f32_fp8_e32 v[176:177], v14
	v_cvt_pk_f32_fp8_sdwa v[178:179], v14 src0_sel:WORD_1
	v_cvt_pk_f32_fp8_e32 v[180:181], v15
	v_cvt_pk_f32_fp8_sdwa v[182:183], v15 src0_sel:WORD_1
	v_pk_mul_f32 v[186:187], v[168:169], v[80:81]
	v_pk_fma_f32 v[186:187], v[170:171], v[82:83], v[186:187]
	v_pk_fma_f32 v[186:187], v[172:173], v[84:85], v[186:187]
	v_pk_fma_f32 v[186:187], v[174:175], v[86:87], v[186:187]
	v_pk_fma_f32 v[186:187], v[176:177], v[88:89], v[186:187]
	v_pk_fma_f32 v[186:187], v[178:179], v[90:91], v[186:187]
	v_pk_fma_f32 v[186:187], v[180:181], v[92:93], v[186:187]
	v_pk_fma_f32 v[186:187], v[182:183], v[94:95], v[186:187]
	v_add_f32_e32 v115, v186, v187
	s_waitcnt vmcnt(11)
	v_cvt_pk_f32_fp8_e32 v[168:169], v16
	v_cvt_pk_f32_fp8_sdwa v[170:171], v16 src0_sel:WORD_1
	v_cvt_pk_f32_fp8_e32 v[172:173], v17
	v_cvt_pk_f32_fp8_sdwa v[174:175], v17 src0_sel:WORD_1
	v_cvt_pk_f32_fp8_e32 v[176:177], v18
	v_cvt_pk_f32_fp8_sdwa v[178:179], v18 src0_sel:WORD_1
	v_cvt_pk_f32_fp8_e32 v[180:181], v19
	v_cvt_pk_f32_fp8_sdwa v[182:183], v19 src0_sel:WORD_1
	v_pk_mul_f32 v[184:185], v[168:169], v[80:81]
	v_pk_fma_f32 v[184:185], v[170:171], v[82:83], v[184:185]
	v_pk_fma_f32 v[184:185], v[172:173], v[84:85], v[184:185]
	v_pk_fma_f32 v[184:185], v[174:175], v[86:87], v[184:185]
	v_pk_fma_f32 v[184:185], v[176:177], v[88:89], v[184:185]
	v_pk_fma_f32 v[184:185], v[178:179], v[90:91], v[184:185]
	v_pk_fma_f32 v[184:185], v[180:181], v[92:93], v[184:185]
	v_pk_fma_f32 v[184:185], v[182:183], v[94:95], v[184:185]
	v_add_f32_e32 v116, v184, v185
	s_waitcnt vmcnt(10)
	v_cvt_pk_f32_fp8_e32 v[168:169], v20
	v_cvt_pk_f32_fp8_sdwa v[170:171], v20 src0_sel:WORD_1
	v_cvt_pk_f32_fp8_e32 v[172:173], v21
	v_cvt_pk_f32_fp8_sdwa v[174:175], v21 src0_sel:WORD_1
	v_cvt_pk_f32_fp8_e32 v[176:177], v22
	v_cvt_pk_f32_fp8_sdwa v[178:179], v22 src0_sel:WORD_1
	v_cvt_pk_f32_fp8_e32 v[180:181], v23
	v_cvt_pk_f32_fp8_sdwa v[182:183], v23 src0_sel:WORD_1
	v_pk_mul_f32 v[186:187], v[168:169], v[80:81]
	v_pk_fma_f32 v[186:187], v[170:171], v[82:83], v[186:187]
	v_pk_fma_f32 v[186:187], v[172:173], v[84:85], v[186:187]
	v_pk_fma_f32 v[186:187], v[174:175], v[86:87], v[186:187]
	v_pk_fma_f32 v[186:187], v[176:177], v[88:89], v[186:187]
	v_pk_fma_f32 v[186:187], v[178:179], v[90:91], v[186:187]
	v_pk_fma_f32 v[186:187], v[180:181], v[92:93], v[186:187]
	v_pk_fma_f32 v[186:187], v[182:183], v[94:95], v[186:187]
	v_add_f32_e32 v117, v186, v187
	s_waitcnt vmcnt(9)
	v_cvt_pk_f32_fp8_e32 v[168:169], v24
	v_cvt_pk_f32_fp8_sdwa v[170:171], v24 src0_sel:WORD_1
	v_cvt_pk_f32_fp8_e32 v[172:173], v25
	v_cvt_pk_f32_fp8_sdwa v[174:175], v25 src0_sel:WORD_1
	v_cvt_pk_f32_fp8_e32 v[176:177], v26
	v_cvt_pk_f32_fp8_sdwa v[178:179], v26 src0_sel:WORD_1
	v_cvt_pk_f32_fp8_e32 v[180:181], v27
	v_cvt_pk_f32_fp8_sdwa v[182:183], v27 src0_sel:WORD_1
	v_pk_mul_f32 v[184:185], v[168:169], v[80:81]
	v_pk_fma_f32 v[184:185], v[170:171], v[82:83], v[184:185]
	v_pk_fma_f32 v[184:185], v[172:173], v[84:85], v[184:185]
	v_pk_fma_f32 v[184:185], v[174:175], v[86:87], v[184:185]
	v_pk_fma_f32 v[184:185], v[176:177], v[88:89], v[184:185]
	v_pk_fma_f32 v[184:185], v[178:179], v[90:91], v[184:185]
	v_pk_fma_f32 v[184:185], v[180:181], v[92:93], v[184:185]
	v_pk_fma_f32 v[184:185], v[182:183], v[94:95], v[184:185]
	v_add_f32_e32 v118, v184, v185
	s_waitcnt vmcnt(8)
	v_cvt_pk_f32_fp8_e32 v[168:169], v28
	v_cvt_pk_f32_fp8_sdwa v[170:171], v28 src0_sel:WORD_1
	v_cvt_pk_f32_fp8_e32 v[172:173], v29
	v_cvt_pk_f32_fp8_sdwa v[174:175], v29 src0_sel:WORD_1
	v_cvt_pk_f32_fp8_e32 v[176:177], v30
	v_cvt_pk_f32_fp8_sdwa v[178:179], v30 src0_sel:WORD_1
	v_cvt_pk_f32_fp8_e32 v[180:181], v31
	v_cvt_pk_f32_fp8_sdwa v[182:183], v31 src0_sel:WORD_1
	v_pk_mul_f32 v[186:187], v[168:169], v[80:81]
	v_pk_fma_f32 v[186:187], v[170:171], v[82:83], v[186:187]
	v_pk_fma_f32 v[186:187], v[172:173], v[84:85], v[186:187]
	v_pk_fma_f32 v[186:187], v[174:175], v[86:87], v[186:187]
	v_pk_fma_f32 v[186:187], v[176:177], v[88:89], v[186:187]
	v_pk_fma_f32 v[186:187], v[178:179], v[90:91], v[186:187]
	v_pk_fma_f32 v[186:187], v[180:181], v[92:93], v[186:187]
	v_pk_fma_f32 v[186:187], v[182:183], v[94:95], v[186:187]
	v_add_f32_e32 v119, v186, v187
	s_waitcnt vmcnt(7)
	v_cvt_pk_f32_fp8_e32 v[168:169], v32
	v_cvt_pk_f32_fp8_sdwa v[170:171], v32 src0_sel:WORD_1
	v_cvt_pk_f32_fp8_e32 v[172:173], v33
	v_cvt_pk_f32_fp8_sdwa v[174:175], v33 src0_sel:WORD_1
	v_cvt_pk_f32_fp8_e32 v[176:177], v34
	v_cvt_pk_f32_fp8_sdwa v[178:179], v34 src0_sel:WORD_1
	v_cvt_pk_f32_fp8_e32 v[180:181], v35
	v_cvt_pk_f32_fp8_sdwa v[182:183], v35 src0_sel:WORD_1
	v_pk_mul_f32 v[184:185], v[168:169], v[80:81]
	v_pk_fma_f32 v[184:185], v[170:171], v[82:83], v[184:185]
	v_pk_fma_f32 v[184:185], v[172:173], v[84:85], v[184:185]
	v_pk_fma_f32 v[184:185], v[174:175], v[86:87], v[184:185]
	v_pk_fma_f32 v[184:185], v[176:177], v[88:89], v[184:185]
	v_pk_fma_f32 v[184:185], v[178:179], v[90:91], v[184:185]
	v_pk_fma_f32 v[184:185], v[180:181], v[92:93], v[184:185]
	v_pk_fma_f32 v[184:185], v[182:183], v[94:95], v[184:185]
	v_add_f32_e32 v120, v184, v185
	s_waitcnt vmcnt(6)
	v_cvt_pk_f32_fp8_e32 v[168:169], v36
	v_cvt_pk_f32_fp8_sdwa v[170:171], v36 src0_sel:WORD_1
	v_cvt_pk_f32_fp8_e32 v[172:173], v37
	v_cvt_pk_f32_fp8_sdwa v[174:175], v37 src0_sel:WORD_1
	v_cvt_pk_f32_fp8_e32 v[176:177], v38
	v_cvt_pk_f32_fp8_sdwa v[178:179], v38 src0_sel:WORD_1
	v_cvt_pk_f32_fp8_e32 v[180:181], v39
	v_cvt_pk_f32_fp8_sdwa v[182:183], v39 src0_sel:WORD_1
	v_pk_mul_f32 v[186:187], v[168:169], v[80:81]
	v_pk_fma_f32 v[186:187], v[170:171], v[82:83], v[186:187]
	v_pk_fma_f32 v[186:187], v[172:173], v[84:85], v[186:187]
	v_pk_fma_f32 v[186:187], v[174:175], v[86:87], v[186:187]
	v_pk_fma_f32 v[186:187], v[176:177], v[88:89], v[186:187]
	v_pk_fma_f32 v[186:187], v[178:179], v[90:91], v[186:187]
	v_pk_fma_f32 v[186:187], v[180:181], v[92:93], v[186:187]
	v_pk_fma_f32 v[186:187], v[182:183], v[94:95], v[186:187]
	v_add_f32_e32 v121, v186, v187
	s_waitcnt vmcnt(5)
	v_cvt_pk_f32_fp8_e32 v[168:169], v40
	v_cvt_pk_f32_fp8_sdwa v[170:171], v40 src0_sel:WORD_1
	v_cvt_pk_f32_fp8_e32 v[172:173], v41
	v_cvt_pk_f32_fp8_sdwa v[174:175], v41 src0_sel:WORD_1
	v_cvt_pk_f32_fp8_e32 v[176:177], v42
	v_cvt_pk_f32_fp8_sdwa v[178:179], v42 src0_sel:WORD_1
	v_cvt_pk_f32_fp8_e32 v[180:181], v43
	v_cvt_pk_f32_fp8_sdwa v[182:183], v43 src0_sel:WORD_1
	v_pk_mul_f32 v[184:185], v[168:169], v[80:81]
	v_pk_fma_f32 v[184:185], v[170:171], v[82:83], v[184:185]
	v_pk_fma_f32 v[184:185], v[172:173], v[84:85], v[184:185]
	v_pk_fma_f32 v[184:185], v[174:175], v[86:87], v[184:185]
	v_pk_fma_f32 v[184:185], v[176:177], v[88:89], v[184:185]
	v_pk_fma_f32 v[184:185], v[178:179], v[90:91], v[184:185]
	v_pk_fma_f32 v[184:185], v[180:181], v[92:93], v[184:185]
	v_pk_fma_f32 v[184:185], v[182:183], v[94:95], v[184:185]
	v_add_f32_e32 v122, v184, v185
	s_waitcnt vmcnt(4)
	v_cvt_pk_f32_fp8_e32 v[168:169], v44
	v_cvt_pk_f32_fp8_sdwa v[170:171], v44 src0_sel:WORD_1
	v_cvt_pk_f32_fp8_e32 v[172:173], v45
	v_cvt_pk_f32_fp8_sdwa v[174:175], v45 src0_sel:WORD_1
	v_cvt_pk_f32_fp8_e32 v[176:177], v46
	v_cvt_pk_f32_fp8_sdwa v[178:179], v46 src0_sel:WORD_1
	v_cvt_pk_f32_fp8_e32 v[180:181], v47
	v_cvt_pk_f32_fp8_sdwa v[182:183], v47 src0_sel:WORD_1
	v_pk_mul_f32 v[186:187], v[168:169], v[80:81]
	v_pk_fma_f32 v[186:187], v[170:171], v[82:83], v[186:187]
	v_pk_fma_f32 v[186:187], v[172:173], v[84:85], v[186:187]
	v_pk_fma_f32 v[186:187], v[174:175], v[86:87], v[186:187]
	v_pk_fma_f32 v[186:187], v[176:177], v[88:89], v[186:187]
	v_pk_fma_f32 v[186:187], v[178:179], v[90:91], v[186:187]
	v_pk_fma_f32 v[186:187], v[180:181], v[92:93], v[186:187]
	v_pk_fma_f32 v[186:187], v[182:183], v[94:95], v[186:187]
	v_add_f32_e32 v123, v186, v187
	s_waitcnt vmcnt(3)
	v_cvt_pk_f32_fp8_e32 v[168:169], v48
	v_cvt_pk_f32_fp8_sdwa v[170:171], v48 src0_sel:WORD_1
	v_cvt_pk_f32_fp8_e32 v[172:173], v49
	v_cvt_pk_f32_fp8_sdwa v[174:175], v49 src0_sel:WORD_1
	v_cvt_pk_f32_fp8_e32 v[176:177], v50
	v_cvt_pk_f32_fp8_sdwa v[178:179], v50 src0_sel:WORD_1
	v_cvt_pk_f32_fp8_e32 v[180:181], v51
	v_cvt_pk_f32_fp8_sdwa v[182:183], v51 src0_sel:WORD_1
	v_pk_mul_f32 v[184:185], v[168:169], v[80:81]
	v_pk_fma_f32 v[184:185], v[170:171], v[82:83], v[184:185]
	v_pk_fma_f32 v[184:185], v[172:173], v[84:85], v[184:185]
	v_pk_fma_f32 v[184:185], v[174:175], v[86:87], v[184:185]
	v_pk_fma_f32 v[184:185], v[176:177], v[88:89], v[184:185]
	v_pk_fma_f32 v[184:185], v[178:179], v[90:91], v[184:185]
	v_pk_fma_f32 v[184:185], v[180:181], v[92:93], v[184:185]
	v_pk_fma_f32 v[184:185], v[182:183], v[94:95], v[184:185]
	v_add_f32_e32 v124, v184, v185
	s_waitcnt vmcnt(2)
	v_cvt_pk_f32_fp8_e32 v[168:169], v52
	v_cvt_pk_f32_fp8_sdwa v[170:171], v52 src0_sel:WORD_1
	v_cvt_pk_f32_fp8_e32 v[172:173], v53
	v_cvt_pk_f32_fp8_sdwa v[174:175], v53 src0_sel:WORD_1
	v_cvt_pk_f32_fp8_e32 v[176:177], v54
	v_cvt_pk_f32_fp8_sdwa v[178:179], v54 src0_sel:WORD_1
	v_cvt_pk_f32_fp8_e32 v[180:181], v55
	v_cvt_pk_f32_fp8_sdwa v[182:183], v55 src0_sel:WORD_1
	v_pk_mul_f32 v[186:187], v[168:169], v[80:81]
	v_pk_fma_f32 v[186:187], v[170:171], v[82:83], v[186:187]
	v_pk_fma_f32 v[186:187], v[172:173], v[84:85], v[186:187]
	v_pk_fma_f32 v[186:187], v[174:175], v[86:87], v[186:187]
	v_pk_fma_f32 v[186:187], v[176:177], v[88:89], v[186:187]
	v_pk_fma_f32 v[186:187], v[178:179], v[90:91], v[186:187]
	v_pk_fma_f32 v[186:187], v[180:181], v[92:93], v[186:187]
	v_pk_fma_f32 v[186:187], v[182:183], v[94:95], v[186:187]
	v_add_f32_e32 v125, v186, v187
	s_waitcnt vmcnt(1)
	v_cvt_pk_f32_fp8_e32 v[168:169], v56
	v_cvt_pk_f32_fp8_sdwa v[170:171], v56 src0_sel:WORD_1
	v_cvt_pk_f32_fp8_e32 v[172:173], v57
	v_cvt_pk_f32_fp8_sdwa v[174:175], v57 src0_sel:WORD_1
	v_cvt_pk_f32_fp8_e32 v[176:177], v58
	v_cvt_pk_f32_fp8_sdwa v[178:179], v58 src0_sel:WORD_1
	v_cvt_pk_f32_fp8_e32 v[180:181], v59
	v_cvt_pk_f32_fp8_sdwa v[182:183], v59 src0_sel:WORD_1
	v_pk_mul_f32 v[184:185], v[168:169], v[80:81]
	v_pk_fma_f32 v[184:185], v[170:171], v[82:83], v[184:185]
	v_pk_fma_f32 v[184:185], v[172:173], v[84:85], v[184:185]
	v_pk_fma_f32 v[184:185], v[174:175], v[86:87], v[184:185]
	v_pk_fma_f32 v[184:185], v[176:177], v[88:89], v[184:185]
	v_pk_fma_f32 v[184:185], v[178:179], v[90:91], v[184:185]
	v_pk_fma_f32 v[184:185], v[180:181], v[92:93], v[184:185]
	v_pk_fma_f32 v[184:185], v[182:183], v[94:95], v[184:185]
	v_add_f32_e32 v126, v184, v185
	s_waitcnt vmcnt(0)
	v_cvt_pk_f32_fp8_e32 v[168:169], v60
	v_cvt_pk_f32_fp8_sdwa v[170:171], v60 src0_sel:WORD_1
	v_cvt_pk_f32_fp8_e32 v[172:173], v61
	v_cvt_pk_f32_fp8_sdwa v[174:175], v61 src0_sel:WORD_1
	v_cvt_pk_f32_fp8_e32 v[176:177], v62
	v_cvt_pk_f32_fp8_sdwa v[178:179], v62 src0_sel:WORD_1
	v_cvt_pk_f32_fp8_e32 v[180:181], v63
	v_cvt_pk_f32_fp8_sdwa v[182:183], v63 src0_sel:WORD_1
	v_pk_mul_f32 v[186:187], v[168:169], v[80:81]
	v_pk_fma_f32 v[186:187], v[170:171], v[82:83], v[186:187]
	v_pk_fma_f32 v[186:187], v[172:173], v[84:85], v[186:187]
	v_pk_fma_f32 v[186:187], v[174:175], v[86:87], v[186:187]
	v_pk_fma_f32 v[186:187], v[176:177], v[88:89], v[186:187]
	v_pk_fma_f32 v[186:187], v[178:179], v[90:91], v[186:187]
	v_pk_fma_f32 v[186:187], v[180:181], v[92:93], v[186:187]
	v_pk_fma_f32 v[186:187], v[182:183], v[94:95], v[186:187]
	v_add_f32_e32 v127, v186, v187
	s_nop 1
	v_add_f32_dpp v160, v112, v112 row_half_mirror row_mask:0xf bank_mask:0x5
	v_add_f32_dpp v160, v113, v113 row_half_mirror row_mask:0xf bank_mask:0xa
	v_add_f32_dpp v161, v114, v114 row_half_mirror row_mask:0xf bank_mask:0x5
	v_add_f32_dpp v161, v115, v115 row_half_mirror row_mask:0xf bank_mask:0xa
	v_add_f32_dpp v162, v116, v116 row_half_mirror row_mask:0xf bank_mask:0x5
	v_add_f32_dpp v162, v117, v117 row_half_mirror row_mask:0xf bank_mask:0xa
	v_add_f32_dpp v163, v118, v118 row_half_mirror row_mask:0xf bank_mask:0x5
	v_add_f32_dpp v163, v119, v119 row_half_mirror row_mask:0xf bank_mask:0xa
	v_add_f32_dpp v164, v120, v120 row_half_mirror row_mask:0xf bank_mask:0x5
	v_add_f32_dpp v164, v121, v121 row_half_mirror row_mask:0xf bank_mask:0xa
	v_add_f32_dpp v165, v122, v122 row_half_mirror row_mask:0xf bank_mask:0x5
	v_add_f32_dpp v165, v123, v123 row_half_mirror row_mask:0xf bank_mask:0xa
	v_add_f32_dpp v166, v124, v124 row_half_mirror row_mask:0xf bank_mask:0x5
	v_add_f32_dpp v166, v125, v125 row_half_mirror row_mask:0xf bank_mask:0xa
	v_add_f32_dpp v167, v126, v126 row_half_mirror row_mask:0xf bank_mask:0x5
	v_add_f32_dpp v167, v127, v127 row_half_mirror row_mask:0xf bank_mask:0xa
	ds_read_b128 v[168:171], v210
	ds_read_b128 v[172:175], v210 offset:16
	s_nop 1
	v_add_f32_dpp v160, v160, v160 quad_perm:[1,0,3,2] row_mask:0xf bank_mask:0xf
	v_add_f32_dpp v161, v161, v161 quad_perm:[1,0,3,2] row_mask:0xf bank_mask:0xf
	v_add_f32_dpp v162, v162, v162 quad_perm:[1,0,3,2] row_mask:0xf bank_mask:0xf
	v_add_f32_dpp v163, v163, v163 quad_perm:[1,0,3,2] row_mask:0xf bank_mask:0xf
	v_add_f32_dpp v164, v164, v164 quad_perm:[1,0,3,2] row_mask:0xf bank_mask:0xf
	v_add_f32_dpp v165, v165, v165 quad_perm:[1,0,3,2] row_mask:0xf bank_mask:0xf
	v_add_f32_dpp v166, v166, v166 quad_perm:[1,0,3,2] row_mask:0xf bank_mask:0xf
	v_add_f32_dpp v167, v167, v167 quad_perm:[1,0,3,2] row_mask:0xf bank_mask:0xf
	s_nop 1
	v_add_f32_dpp v160, v160, v160 quad_perm:[2,3,0,1] row_mask:0xf bank_mask:0xf
	v_add_f32_dpp v161, v161, v161 quad_perm:[2,3,0,1] row_mask:0xf bank_mask:0xf
	v_add_f32_dpp v162, v162, v162 quad_perm:[2,3,0,1] row_mask:0xf bank_mask:0xf
	v_add_f32_dpp v163, v163, v163 quad_perm:[2,3,0,1] row_mask:0xf bank_mask:0xf
	v_add_f32_dpp v164, v164, v164 quad_perm:[2,3,0,1] row_mask:0xf bank_mask:0xf
	v_add_f32_dpp v165, v165, v165 quad_perm:[2,3,0,1] row_mask:0xf bank_mask:0xf
	v_add_f32_dpp v166, v166, v166 quad_perm:[2,3,0,1] row_mask:0xf bank_mask:0xf
	v_add_f32_dpp v167, v167, v167 quad_perm:[2,3,0,1] row_mask:0xf bank_mask:0xf
	s_waitcnt lgkmcnt(0)
	v_fmac_f32_e32 v168, v208, v160
	v_fmac_f32_e32 v169, v208, v161
	v_fmac_f32_e32 v170, v208, v162
	v_fmac_f32_e32 v171, v208, v163
	v_fmac_f32_e32 v172, v208, v164
	v_fmac_f32_e32 v173, v208, v165
	v_fmac_f32_e32 v174, v208, v166
	v_fmac_f32_e32 v175, v208, v167
	ds_write_b128 v210, v[168:171]
	ds_write_b128 v210, v[172:175] offset:16
	s_add_i32 s17, s17, 1
	s_cmp_lt_i32 s17, s43
	s_cbranch_scc1 .Lpb_unit
	s_add_i32 s16, s16, 1
	s_cmp_lt_i32 s16, 8
	s_cbranch_scc1 .Lpb_slice
	v_and_b32_e32 v160, 63, v218
	v_and_b32_e32 v161, 0x30, v160
	v_and_b32_e32 v162, 1, v160
	v_bfe_u32 v163, v160, 1, 3
	v_lshl_add_u32 v161, v162, 3, v161
	v_add_u32_e32 v161, v161, v163
	v_lshlrev_b32_e32 v161, 2, v161
	v_lshlrev_b32_e32 v160, 2, v160
	v_sub_u32_e32 v162, v202, v160
	v_add_u32_e32 v161, v161, v162
	v_add_u32_e32 v161, 0x2400, v161
	s_mov_b32 s17, 0
